# software-pipelined final RMSNorm row loop (all row loads issued together, next row prefetched)
# baseline (speedup 1.0000x reference)
.LBB0_3119:
	global_load_dwordx4 v[40:43], v[2:3], off
	global_load_dwordx4 v[44:47], v[2:3], off offset:1024
	global_load_dwordx4 v[48:51], v[2:3], off offset:2048
	global_load_dwordx4 v[52:55], v[2:3], off offset:3072
	s_add_u32 s14, s2, s6
	s_addc_u32 s15, s3, s7
	v_lshl_add_u64 v[28:29], s[2:3], 0, v[6:7]
	global_load_dwordx4 v[56:59], v1, s[14:15]
	global_load_dwordx4 v[60:63], v1, s[14:15] offset:16
	global_load_dwordx4 v[64:67], v1, s[14:15] offset:32
	global_load_dwordx4 v[68:71], v1, s[14:15] offset:48
	global_load_dwordx2 v[72:73], v[28:29], off offset:-1024
	global_load_dwordx2 v[74:75], v[28:29], off offset:-512
	global_load_dwordx2 v[76:77], v[28:29], off
	global_load_dwordx2 v[78:79], v[28:29], off offset:512
	s_waitcnt vmcnt(0)
.Lfn_row:
	v_mov_b64_e32 v[8:9], v[56:57]
	v_mov_b64_e32 v[10:11], v[58:59]
	v_mov_b64_e32 v[12:13], v[60:61]
	v_mov_b64_e32 v[14:15], v[62:63]
	v_mov_b64_e32 v[16:17], v[64:65]
	v_mov_b64_e32 v[18:19], v[66:67]
	v_mov_b64_e32 v[20:21], v[68:69]
	v_mov_b64_e32 v[22:23], v[70:71]
	v_mov_b64_e32 v[30:31], v[72:73]
	v_mov_b64_e32 v[32:33], v[74:75]
	v_mov_b64_e32 v[34:35], v[76:77]
	v_mov_b64_e32 v[36:37], v[78:79]
	s_add_i32 s12, s12, s0
	s_add_u32 s6, s6, s8
	s_addc_u32 s7, s7, s9
	v_lshl_add_u64 v[6:7], v[6:7], 0, s[10:11]
	s_cmpk_gt_i32 s12, 0x7fff
	s_cbranch_scc1 .Lfn_compute
	s_add_u32 s14, s2, s6
	s_addc_u32 s15, s3, s7
	v_lshl_add_u64 v[28:29], s[2:3], 0, v[6:7]
	global_load_dwordx4 v[56:59], v1, s[14:15]
	global_load_dwordx4 v[60:63], v1, s[14:15] offset:16
	global_load_dwordx4 v[64:67], v1, s[14:15] offset:32
	global_load_dwordx4 v[68:71], v1, s[14:15] offset:48
	global_load_dwordx2 v[72:73], v[28:29], off offset:-1024
	global_load_dwordx2 v[74:75], v[28:29], off offset:-512
	global_load_dwordx2 v[76:77], v[28:29], off
	global_load_dwordx2 v[78:79], v[28:29], off offset:512
.Lfn_compute:
	v_pk_add_f32 v[10:11], v[10:11], v[14:15]
	v_pk_add_f32 v[8:9], v[8:9], v[12:13]
	v_pk_add_f32 v[12:13], v[18:19], v[22:23]
	v_pk_add_f32 v[14:15], v[16:17], v[20:21]
	v_pk_add_f32 v[10:11], v[10:11], v[12:13]
	v_pk_add_f32 v[8:9], v[8:9], v[14:15]
	v_mov_b32_e32 v13, v10
	v_mov_b32_e32 v12, v9
	v_mov_b32_e32 v9, v11
	v_pk_add_f32 v[8:9], v[12:13], v[8:9]
	v_add_f32_e32 v8, v8, v9
	v_fmamk_f32 v8, v8, 0x3a800000, v0
	v_mul_f32_e32 v9, 0x4b800000, v8
	v_cmp_gt_f32_e32 vcc, s1, v8
	v_lshlrev_b32_e32 v16, 16, v30
	v_and_b32_e32 v17, 0xffff0000, v30
	v_cndmask_b32_e32 v8, v8, v9, vcc
	v_rsq_f32_e32 v8, v8
	v_lshlrev_b32_e32 v18, 16, v31
	v_and_b32_e32 v19, 0xffff0000, v31
	v_mul_f32_e32 v9, 0x45800000, v8
	v_cndmask_b32_e32 v12, v8, v9, vcc
	v_pk_mul_f32 v[84:85], v[12:13], v[16:17] op_sel_hi:[0,1]
	v_pk_mul_f32 v[86:87], v[12:13], v[18:19] op_sel_hi:[0,1]
	v_pk_mul_f32 v[86:87], v[42:43], v[86:87]
	v_pk_mul_f32 v[84:85], v[40:41], v[84:85]
	global_store_dwordx4 v[4:5], v[84:87], off offset:-3072
	v_lshlrev_b32_e32 v16, 16, v32
	v_and_b32_e32 v17, 0xffff0000, v32
	v_lshlrev_b32_e32 v18, 16, v33
	v_and_b32_e32 v19, 0xffff0000, v33
	v_pk_mul_f32 v[88:89], v[12:13], v[16:17] op_sel_hi:[0,1]
	v_pk_mul_f32 v[90:91], v[12:13], v[18:19] op_sel_hi:[0,1]
	v_pk_mul_f32 v[90:91], v[46:47], v[90:91]
	v_pk_mul_f32 v[88:89], v[44:45], v[88:89]
	global_store_dwordx4 v[4:5], v[88:91], off offset:-2048
	v_lshlrev_b32_e32 v16, 16, v34
	v_and_b32_e32 v17, 0xffff0000, v34
	v_lshlrev_b32_e32 v18, 16, v35
	v_and_b32_e32 v19, 0xffff0000, v35
	v_pk_mul_f32 v[92:93], v[12:13], v[16:17] op_sel_hi:[0,1]
	v_pk_mul_f32 v[94:95], v[12:13], v[18:19] op_sel_hi:[0,1]
	v_pk_mul_f32 v[94:95], v[50:51], v[94:95]
	v_pk_mul_f32 v[92:93], v[48:49], v[92:93]
	global_store_dwordx4 v[4:5], v[92:95], off offset:-1024
	v_lshlrev_b32_e32 v16, 16, v36
	v_and_b32_e32 v17, 0xffff0000, v36
	v_lshlrev_b32_e32 v18, 16, v37
	v_and_b32_e32 v19, 0xffff0000, v37
	v_pk_mul_f32 v[96:97], v[12:13], v[16:17] op_sel_hi:[0,1]
	v_pk_mul_f32 v[98:99], v[12:13], v[18:19] op_sel_hi:[0,1]
	v_pk_mul_f32 v[98:99], v[54:55], v[98:99]
	v_pk_mul_f32 v[96:97], v[52:53], v[96:97]
	global_store_dwordx4 v[4:5], v[96:99], off
	v_lshl_add_u64 v[4:5], v[4:5], 0, s[4:5]
	s_cmpk_gt_i32 s12, 0x7fff
	s_cbranch_scc1 .LBB0_3120
	s_waitcnt vmcnt(4)
	s_branch .Lfn_row
